# v44 with three early decode pulls on group 0 of the non-preparing workgroups
# speedup vs baseline: 1.0363x; 1.0088x over previous
; #define LAS __attribute__((address_space(3)))
; __device__ __forceinline__ void p3_scan_and_sb(const Params& P, float* lds) {
;     ...
;     } else {
;         const int grp = wave >> 2, gw = wave & 3;
;         volatile LAS unsigned* gctl = (volatile LAS unsigned*)((LAS unsigned char*)lds + LDS_CTL + 32);
;         if (tid < 8) gctl[tid] = 0u;
;         __syncthreads();
;         sba::Grp4 G; G.ctr = gctl + grp; G.gen = 0u;
;         if (grp == 1) sb_decode_wave_loop(P, lds);
.LBB0_939:
	s_cmp_lt_i32 s60, 4
	s_cselect_b64 s[0:1], -1, 0
	s_cmp_gt_i32 s61, 3
	s_cselect_b64 s[2:3], -1, 0
	s_and_b64 s[34:35], s[0:1], s[2:3]
	s_andn2_b64 vcc, exec, s[34:35]
	s_cbranch_vccnz .LBB0_1576
	v_writelane_b32 v252, s34, 54
	s_cmpk_lt_u32 s56, 0x60
	v_and_b32_e32 v1, 63, v0
	v_writelane_b32 v252, s35, 55
	v_writelane_b32 v252, s80, 56
	s_cselect_b64 s[52:53], -1, 0
	s_cmpk_gt_u32 s56, 0x5f
	v_writelane_b32 v252, s81, 57
	v_writelane_b32 v252, s56, 53
	v_writelane_b32 v252, s60, 51
	s_mov_b64 s[0:1], -1
	s_waitcnt vmcnt(0)
	v_writelane_b32 v252, s61, 52
	s_barrier
	v_writelane_b32 v252, s57, 50
	s_cbranch_scc0 .LBB0_1203
	v_writelane_b32 v252, s52, 58
	v_cmp_gt_u32_e32 vcc, 8, v0
	s_nop 0
	v_writelane_b32 v252, s53, 59
	s_and_saveexec_b64 s[0:1], vcc
	v_lshl_add_u32 v2, v0, 2, 0
	v_add_u32_e32 v2, 0x26020, v2
	v_mov_b32_e32 v3, 0
	ds_write_b32 v2, v3
	s_or_b64 exec, exec, s[0:1]
	v_lshrrev_b32_e32 v94, 8, v0
	s_waitcnt lgkmcnt(0)
	s_barrier
	v_cmp_eq_u32_e32 vcc, 1, v94
	s_mov_b64 s[0:1], exec
	v_writelane_b32 v252, s0, 60
	s_nop 1
	v_writelane_b32 v252, s1, 61
	s_cmpk_gt_u32 s56, 0xaa
	s_cselect_b64 s[2:3], exec, 0
	s_or_b64 vcc, vcc, s[2:3]
	s_and_b64 s[0:1], s[0:1], vcc
	s_mov_b64 exec, s[0:1]
	s_cbranch_execz .LBB0_1092
	v_readfirstlane_b32 s2, v94
	s_cmp_eq_u32 s2, 0
	s_cselect_b32 s100, 2, 0x7fffffff
	s_add_u32 s0, s78, 0x3900
	s_addc_u32 s1, s79, 0
	v_writelane_b32 v252, s0, 62
	v_mov_b32_e32 v95, 0
	v_cmp_eq_u32_e64 s[4:5], 0, v1
	v_writelane_b32 v252, s1, 63
	s_and_saveexec_b64 s[0:1], s[4:5]
	v_readlane_b32 s22, v252, 48
	v_readlane_b32 s23, v252, 49
	s_cbranch_execz .LBB0_948
	s_mov_b64 s[6:7], exec
	v_mbcnt_lo_u32_b32 v2, s6, 0
	v_mbcnt_hi_u32_b32 v2, s7, v2
	v_cmp_eq_u32_e32 vcc, 0, v2
	s_and_saveexec_b64 s[2:3], vcc
	s_cbranch_execz .LBB0_947
	s_bcnt1_i32_b64 s6, s[6:7]
	s_lshl_b32 s6, s6, 1
	v_mov_b32_e32 v4, s6
	v_readlane_b32 s6, v252, 62
	v_mov_b32_e32 v3, 0
	v_readlane_b32 s7, v252, 63
	s_nop 4
	global_atomic_add v3, v3, v4, s[6:7] sc0
